# v12 + nt cache policy on the FFN1 activation stores of the P1 epilogue (write-once stream)
# speedup vs baseline: 1.0033x; 1.0033x over previous
.LBB0_645:
	s_lshl_b32 s18, s68, 8
	v_mov_b32_e32 v145, v136
	s_add_i32 s18, s18, s56
	v_pk_mul_f32 v[152:153], v[108:109], v[112:113]
	v_and_or_b32 v134, v145, 15, s18
	v_ashrrev_i32_e32 v135, 31, v134
	v_lshl_add_u64 v[148:149], v[134:135], 2, s[36:37]
	global_load_dword v135, v[148:149], off
	global_load_dword v147, v[148:149], off offset:64
	global_load_dword v156, v[148:149], off offset:128
	global_load_dword v157, v[148:149], off offset:192
	global_load_dword v158, v[148:149], off offset:512
	global_load_dword v159, v[148:149], off offset:576
	global_load_dword v160, v[148:149], off offset:640
	global_load_dword v161, v[148:149], off offset:704
	s_lshl_b32 s18, s67, 7
	v_lshrrev_b32_e32 v108, 1, v145
	v_and_or_b32 v108, v108, 24, s18
	v_or_b32_e32 v108, s57, v108
	v_pk_mul_f32 v[150:151], v[122:123], v[114:115]
	v_mov_b64_e32 v[122:123], s[38:39]
	v_ashrrev_i32_e32 v109, 31, v108
	v_pk_mul_f32 v[148:149], v[124:125], v[116:117]
	v_mad_i64_i32 v[124:125], s[18:19], v134, s62, v[122:123]
	v_lshlrev_b64 v[108:109], 1, v[108:109]
	v_lshl_add_u64 v[154:155], v[124:125], 0, v[108:109]
	v_pk_mul_f32 v[128:129], v[128:129], v[120:121]
	v_pk_mul_f32 v[126:127], v[126:127], v[118:119]
	v_pk_mul_f32 v[100:101], v[100:101], v[104:105]
	v_pk_mul_f32 v[98:99], v[98:99], v[102:103]
	v_pk_mul_f32 v[106:107], v[106:107], v[110:111]
	v_pk_mul_f32 v[92:93], v[92:93], v[96:97]
	v_pk_mul_f32 v[90:91], v[90:91], v[94:95]
	v_pk_mul_f32 v[84:85], v[84:85], v[88:89]
	v_pk_mul_f32 v[82:83], v[82:83], v[86:87]
	v_pk_mul_f32 v[76:77], v[76:77], v[80:81]
	v_pk_mul_f32 v[74:75], v[74:75], v[78:79]
	v_pk_mul_f32 v[60:61], v[60:61], v[64:65]
	v_pk_mul_f32 v[58:59], v[58:59], v[62:63]
	v_pk_mul_f32 v[52:53], v[52:53], v[56:57]
	v_pk_mul_f32 v[50:51], v[50:51], v[54:55]
	v_pk_mul_f32 v[44:45], v[44:45], v[48:49]
	v_pk_mul_f32 v[42:43], v[42:43], v[46:47]
	v_pk_mul_f32 v[36:37], v[36:37], v[40:41]
	v_pk_mul_f32 v[34:35], v[34:35], v[38:39]
	v_pk_mul_f32 v[28:29], v[28:29], v[32:33]
	v_pk_mul_f32 v[26:27], v[26:27], v[30:31]
	v_pk_mul_f32 v[20:21], v[20:21], v[24:25]
	v_pk_mul_f32 v[18:19], v[18:19], v[22:23]
	v_pk_mul_f32 v[12:13], v[12:13], v[16:17]
	v_pk_mul_f32 v[10:11], v[10:11], v[14:15]
	v_pk_mul_f32 v[4:5], v[4:5], v[8:9]
	v_pk_mul_f32 v[2:3], v[2:3], v[6:7]
	s_andn2_b64 vcc, exec, s[4:5]
	s_mov_b64 s[4:5], -1
	s_waitcnt vmcnt(7)
	v_cvt_f32_u32_e32 v124, v135
	s_waitcnt vmcnt(6)
	v_cvt_f32_u32_e32 v125, v147
	s_waitcnt vmcnt(5)
	v_cvt_f32_u32_e32 v135, v156
	s_waitcnt vmcnt(4)
	v_cvt_f32_u32_e32 v145, v157
	v_mul_f32_e32 v124, 0x38800000, v124
	s_waitcnt vmcnt(2)
	v_cvt_f32_u32_e32 v156, v159
	s_waitcnt vmcnt(1)
	v_cvt_f32_u32_e32 v157, v160
	v_mul_f32_e32 v159, 0x38800000, v125
	v_fmamk_f32 v124, v124, 0x39800000, v144
	v_cvt_f32_u32_e32 v147, v158
	v_mul_f32_e32 v125, 0x38800000, v157
	v_rsq_f32_e32 v157, v124
	v_fmamk_f32 v124, v159, 0x39800000, v144
	v_rsq_f32_e32 v159, v124
	s_waitcnt vmcnt(0)
	v_cvt_f32_u32_e32 v158, v161
	v_mul_f32_e32 v161, 0x38800000, v156
	v_mul_f32_e32 v156, 0xbfb8aa3b, v157
	v_mul_f32_e32 v160, 0xbfb8aa3b, v159
	v_pk_mul_f32 v[120:121], v[120:121], v[156:157] op_sel_hi:[1,0]
	v_pk_mul_f32 v[118:119], v[118:119], v[156:157] op_sel_hi:[1,0]
	v_pk_mul_f32 v[116:117], v[116:117], v[156:157] op_sel_hi:[1,0]
	v_pk_mul_f32 v[114:115], v[114:115], v[156:157] op_sel_hi:[1,0]
	v_pk_mul_f32 v[112:113], v[112:113], v[160:161] op_sel_hi:[1,0]
	v_exp_f32_e32 v118, v118
	v_exp_f32_e32 v119, v119
	v_exp_f32_e32 v120, v120
	v_exp_f32_e32 v121, v121
	v_exp_f32_e32 v114, v114
	v_exp_f32_e32 v115, v115
	v_exp_f32_e32 v116, v116
	v_exp_f32_e32 v117, v117
	v_exp_f32_e32 v112, v112
	v_exp_f32_e32 v113, v113
	v_mul_f32_e32 v124, 0x38800000, v158
	v_mul_f32_e32 v158, v157, v157
	v_add_f32_e32 v118, 1.0, v118
	v_add_f32_e32 v119, 1.0, v119
	v_add_f32_e32 v120, 1.0, v120
	v_add_f32_e32 v121, 1.0, v121
	v_mul_f32_e32 v162, v159, v159
	v_pk_mul_f32 v[126:127], v[126:127], v[158:159] op_sel_hi:[1,0]
	v_pk_mul_f32 v[128:129], v[128:129], v[158:159] op_sel_hi:[1,0]
	v_pk_mul_f32 v[150:151], v[150:151], v[158:159] op_sel_hi:[1,0]
	v_pk_mul_f32 v[148:149], v[148:149], v[158:159] op_sel_hi:[1,0]
	v_add_f32_e32 v158, 1.0, v114
	v_add_f32_e32 v159, 1.0, v115
	v_add_f32_e32 v163, 1.0, v116
	v_add_f32_e32 v164, 1.0, v117
	v_add_f32_e32 v165, 1.0, v112
	v_add_f32_e32 v166, 1.0, v113
	v_rcp_f32_e32 v112, v118
	v_rcp_f32_e32 v113, v119
	v_rcp_f32_e32 v114, v120
	v_rcp_f32_e32 v115, v121
	v_rcp_f32_e32 v116, v158
	v_rcp_f32_e32 v117, v159
	v_rcp_f32_e32 v118, v163
	v_rcp_f32_e32 v119, v164
	v_pk_mul_f32 v[114:115], v[128:129], v[114:115]
	v_pk_mul_f32 v[112:113], v[126:127], v[112:113]
	v_pk_mul_f32 v[116:117], v[150:151], v[116:117]
	v_pk_mul_f32 v[118:119], v[148:149], v[118:119]
	v_cvt_pk_bf16_f32 v112, v112, v113
	v_cvt_pk_bf16_f32 v113, v114, v115
	v_cvt_pk_bf16_f32 v114, v116, v117
	v_pk_mul_f32 v[156:157], v[110:111], v[160:161] op_sel_hi:[1,0]
	v_cvt_pk_bf16_f32 v115, v118, v119
	global_store_dwordx4 v[154:155], v[112:115], off nt
	v_exp_f32_e32 v156, v156
	v_exp_f32_e32 v157, v157
	v_pk_mul_f32 v[112:113], v[102:103], v[160:161] op_sel_hi:[1,0]
	v_pk_mul_f32 v[114:115], v[104:105], v[160:161] op_sel_hi:[1,0]
	v_exp_f32_e32 v112, v112
	v_exp_f32_e32 v113, v113
	v_exp_f32_e32 v114, v114
	v_exp_f32_e32 v115, v115
	v_add_f32_e32 v112, 1.0, v112
	v_add_f32_e32 v113, 1.0, v113
	v_add_f32_e32 v114, 1.0, v114
	v_add_f32_e32 v115, 1.0, v115
	v_add_f32_e32 v156, 1.0, v156
	v_add_f32_e32 v157, 1.0, v157
	v_rcp_f32_e32 v112, v112
	v_rcp_f32_e32 v113, v113
	v_rcp_f32_e32 v114, v114
	v_rcp_f32_e32 v115, v115
	v_rcp_f32_e32 v120, v156
	v_rcp_f32_e32 v121, v157
	v_rcp_f32_e32 v156, v165
	v_rcp_f32_e32 v157, v166
	v_pk_mul_f32 v[98:99], v[98:99], v[162:163] op_sel_hi:[1,0]
	v_pk_mul_f32 v[100:101], v[100:101], v[162:163] op_sel_hi:[1,0]
	v_mul_f32_e32 v135, 0x38800000, v135
	v_pk_mul_f32 v[106:107], v[106:107], v[162:163] op_sel_hi:[1,0]
	v_pk_mul_f32 v[110:111], v[152:153], v[162:163] op_sel_hi:[1,0]
	v_pk_mul_f32 v[102:103], v[100:101], v[114:115]
	v_pk_mul_f32 v[100:101], v[98:99], v[112:113]
	v_pk_mul_f32 v[110:111], v[110:111], v[156:157]
	v_pk_mul_f32 v[106:107], v[106:107], v[120:121]
	v_or_b32_e32 v104, 16, v134
	v_cvt_pk_bf16_f32 v98, v106, v107
	v_cvt_pk_bf16_f32 v99, v110, v111
	v_cvt_pk_bf16_f32 v100, v100, v101
	v_cvt_pk_bf16_f32 v101, v102, v103
	v_fmamk_f32 v102, v135, 0x39800000, v144
	v_rsq_f32_e32 v105, v102
	v_mad_i64_i32 v[102:103], s[18:19], v104, s62, v[122:123]
	v_lshl_add_u64 v[102:103], v[102:103], 0, v[108:109]
	global_store_dwordx4 v[102:103], v[98:101], off nt
	v_mul_f32_e32 v145, 0x38800000, v145
	v_mul_f32_e32 v147, 0x38800000, v147
	v_mul_f32_e32 v98, 0xbfb8aa3b, v105
	v_pk_mul_f32 v[100:101], v[94:95], v[98:99] op_sel_hi:[1,0]
	s_nop 0
	v_exp_f32_e32 v99, v100
	v_exp_f32_e32 v101, v101
	v_mul_f32_e32 v100, v105, v105
	v_pk_mul_f32 v[102:103], v[96:97], v[98:99] op_sel_hi:[1,0]
	v_add_f32_e32 v99, 1.0, v99
	v_rcp_f32_e32 v104, v99
	v_exp_f32_e32 v99, v102
	v_exp_f32_e32 v103, v103
	v_add_f32_e32 v101, 1.0, v101
	v_rcp_f32_e32 v105, v101
	v_add_f32_e32 v99, 1.0, v99
	v_rcp_f32_e32 v102, v99
	v_add_f32_e32 v99, 1.0, v103
	v_pk_mul_f32 v[94:95], v[86:87], v[98:99] op_sel_hi:[1,0]
	v_pk_mul_f32 v[96:97], v[88:89], v[98:99] op_sel_hi:[1,0]
	v_exp_f32_e32 v94, v94
	v_exp_f32_e32 v95, v95
	v_exp_f32_e32 v96, v96
	v_exp_f32_e32 v97, v97
	v_add_f32_e32 v94, 1.0, v94
	v_add_f32_e32 v95, 1.0, v95
	v_add_f32_e32 v96, 1.0, v96
	v_add_f32_e32 v97, 1.0, v97
	v_rcp_f32_e32 v94, v94
	v_rcp_f32_e32 v95, v95
	v_rcp_f32_e32 v96, v96
	v_rcp_f32_e32 v97, v97
	v_rcp_f32_e32 v103, v99
	v_pk_mul_f32 v[82:83], v[82:83], v[100:101] op_sel_hi:[1,0]
	v_pk_mul_f32 v[84:85], v[84:85], v[100:101] op_sel_hi:[1,0]
	v_pk_mul_f32 v[90:91], v[90:91], v[100:101] op_sel_hi:[1,0]
	v_pk_mul_f32 v[92:93], v[92:93], v[100:101] op_sel_hi:[1,0]
	v_pk_mul_f32 v[86:87], v[84:85], v[96:97]
	v_pk_mul_f32 v[84:85], v[82:83], v[94:95]
	v_pk_mul_f32 v[92:93], v[92:93], v[102:103]
	v_pk_mul_f32 v[90:91], v[90:91], v[104:105]
	v_or_b32_e32 v88, 32, v134
	v_cvt_pk_bf16_f32 v82, v90, v91
	v_cvt_pk_bf16_f32 v83, v92, v93
	v_cvt_pk_bf16_f32 v84, v84, v85
	v_cvt_pk_bf16_f32 v85, v86, v87
	v_fmamk_f32 v86, v145, 0x39800000, v144
	v_rsq_f32_e32 v89, v86
	v_mad_i64_i32 v[86:87], s[18:19], v88, s62, v[122:123]
	v_lshl_add_u64 v[86:87], v[86:87], 0, v[108:109]
	global_store_dwordx4 v[86:87], v[82:85], off nt
	s_nop 1
	v_mul_f32_e32 v82, 0xbfb8aa3b, v89
	v_pk_mul_f32 v[84:85], v[78:79], v[82:83] op_sel_hi:[1,0]
	s_nop 0
	v_exp_f32_e32 v83, v84
	v_exp_f32_e32 v85, v85
	v_mul_f32_e32 v84, v89, v89
	v_pk_mul_f32 v[86:87], v[80:81], v[82:83] op_sel_hi:[1,0]
	v_add_f32_e32 v83, 1.0, v83
	v_rcp_f32_e32 v88, v83
	v_exp_f32_e32 v83, v86
	v_exp_f32_e32 v87, v87
	v_add_f32_e32 v85, 1.0, v85
	v_rcp_f32_e32 v89, v85
	v_add_f32_e32 v83, 1.0, v83
	v_rcp_f32_e32 v86, v83
	v_add_f32_e32 v83, 1.0, v87
	v_pk_mul_f32 v[78:79], v[66:67], v[82:83] op_sel_hi:[1,0]
	v_pk_mul_f32 v[80:81], v[68:69], v[82:83] op_sel_hi:[1,0]
	v_exp_f32_e32 v78, v78
	v_exp_f32_e32 v79, v79
	v_exp_f32_e32 v80, v80
	v_exp_f32_e32 v81, v81
	v_add_f32_e32 v78, 1.0, v78
	v_add_f32_e32 v79, 1.0, v79
	v_add_f32_e32 v80, 1.0, v80
	v_add_f32_e32 v81, 1.0, v81
	v_rcp_f32_e32 v78, v78
	v_rcp_f32_e32 v79, v79
	v_rcp_f32_e32 v80, v80
	v_rcp_f32_e32 v81, v81
	v_rcp_f32_e32 v87, v83
	v_pk_mul_f32 v[68:69], v[72:73], v[68:69]
	v_pk_mul_f32 v[66:67], v[70:71], v[66:67]
	v_pk_mul_f32 v[68:69], v[68:69], v[84:85] op_sel_hi:[1,0]
	v_pk_mul_f32 v[66:67], v[66:67], v[84:85] op_sel_hi:[1,0]
	v_pk_mul_f32 v[74:75], v[74:75], v[84:85] op_sel_hi:[1,0]
	v_pk_mul_f32 v[76:77], v[76:77], v[84:85] op_sel_hi:[1,0]
	v_pk_mul_f32 v[70:71], v[68:69], v[80:81]
	v_pk_mul_f32 v[68:69], v[66:67], v[78:79]
	v_or_b32_e32 v72, 48, v134
	v_pk_mul_f32 v[76:77], v[76:77], v[86:87]
	v_pk_mul_f32 v[74:75], v[74:75], v[88:89]
	s_nop 0
	v_cvt_pk_bf16_f32 v66, v74, v75
	v_cvt_pk_bf16_f32 v67, v76, v77
	v_cvt_pk_bf16_f32 v68, v68, v69
	v_cvt_pk_bf16_f32 v69, v70, v71
	v_mad_i64_i32 v[70:71], s[18:19], v72, s62, v[122:123]
	v_fmamk_f32 v72, v147, 0x39800000, v144
	v_rsq_f32_e32 v72, v72
	v_lshl_add_u64 v[70:71], v[70:71], 0, v[108:109]
	global_store_dwordx4 v[70:71], v[66:69], off nt
	s_nop 1
	v_add_u32_e32 v67, 0x80, v134
	v_mul_f32_e32 v66, 0xbfb8aa3b, v72
	v_pk_mul_f32 v[68:69], v[62:63], v[66:67] op_sel_hi:[1,0]
	v_pk_mul_f32 v[70:71], v[64:65], v[66:67] op_sel_hi:[1,0]
	v_exp_f32_e32 v69, v69
	v_pk_mul_f32 v[62:63], v[54:55], v[66:67] op_sel_hi:[1,0]
	v_pk_mul_f32 v[64:65], v[56:57], v[66:67] op_sel_hi:[1,0]
	v_exp_f32_e32 v73, v68
	v_exp_f32_e32 v70, v70
	v_exp_f32_e32 v62, v62
	v_exp_f32_e32 v63, v63
	v_exp_f32_e32 v64, v64
	v_exp_f32_e32 v65, v65
	v_exp_f32_e32 v71, v71
	v_add_f32_e32 v69, 1.0, v69
	v_mul_f32_e32 v68, v72, v72
	v_add_f32_e32 v72, 1.0, v73
	v_rcp_f32_e32 v73, v69
	v_add_f32_e32 v69, 1.0, v70
	v_add_f32_e32 v62, 1.0, v62
	v_add_f32_e32 v63, 1.0, v63
	v_add_f32_e32 v64, 1.0, v64
	v_add_f32_e32 v65, 1.0, v65
	v_rcp_f32_e32 v70, v69
	v_add_f32_e32 v69, 1.0, v71
	v_rcp_f32_e32 v62, v62
	v_rcp_f32_e32 v63, v63
	v_rcp_f32_e32 v64, v64
	v_rcp_f32_e32 v65, v65
	v_rcp_f32_e32 v72, v72
	v_rcp_f32_e32 v71, v69
	v_pk_mul_f32 v[50:51], v[50:51], v[68:69] op_sel_hi:[1,0]
	v_pk_mul_f32 v[52:53], v[52:53], v[68:69] op_sel_hi:[1,0]
	v_pk_mul_f32 v[58:59], v[58:59], v[68:69] op_sel_hi:[1,0]
	v_pk_mul_f32 v[60:61], v[60:61], v[68:69] op_sel_hi:[1,0]
	v_pk_mul_f32 v[54:55], v[52:53], v[64:65]
	v_pk_mul_f32 v[52:53], v[50:51], v[62:63]
	v_pk_mul_f32 v[60:61], v[60:61], v[70:71]
	v_pk_mul_f32 v[58:59], v[58:59], v[72:73]
	s_nop 0
	v_cvt_pk_bf16_f32 v50, v58, v59
	v_cvt_pk_bf16_f32 v51, v60, v61
	v_cvt_pk_bf16_f32 v52, v52, v53
	v_cvt_pk_bf16_f32 v53, v54, v55
	v_fmamk_f32 v54, v161, 0x39800000, v144
	v_rsq_f32_e32 v56, v54
	v_mad_i64_i32 v[54:55], s[18:19], v67, s62, v[122:123]
	v_lshl_add_u64 v[54:55], v[54:55], 0, v[108:109]
	global_store_dwordx4 v[54:55], v[50:53], off nt
	s_nop 1
	v_mul_f32_e32 v50, 0xbfb8aa3b, v56
	v_pk_mul_f32 v[52:53], v[46:47], v[50:51] op_sel_hi:[1,0]
	s_nop 0
	v_exp_f32_e32 v51, v52
	v_mul_f32_e32 v52, v56, v56
	v_exp_f32_e32 v53, v53
	v_pk_mul_f32 v[54:55], v[48:49], v[50:51] op_sel_hi:[1,0]
	v_add_f32_e32 v51, 1.0, v51
	v_rcp_f32_e32 v56, v51
	v_exp_f32_e32 v51, v54
	v_exp_f32_e32 v55, v55
	v_add_f32_e32 v53, 1.0, v53
	v_rcp_f32_e32 v57, v53
	v_add_f32_e32 v51, 1.0, v51
	v_rcp_f32_e32 v54, v51
	v_add_f32_e32 v51, 1.0, v55
	v_pk_mul_f32 v[46:47], v[38:39], v[50:51] op_sel_hi:[1,0]
	v_pk_mul_f32 v[48:49], v[40:41], v[50:51] op_sel_hi:[1,0]
	v_exp_f32_e32 v46, v46
	v_exp_f32_e32 v47, v47
	v_exp_f32_e32 v48, v48
	v_exp_f32_e32 v49, v49
	v_add_f32_e32 v46, 1.0, v46
	v_add_f32_e32 v47, 1.0, v47
	v_add_f32_e32 v48, 1.0, v48
	v_add_f32_e32 v49, 1.0, v49
	v_rcp_f32_e32 v46, v46
	v_rcp_f32_e32 v47, v47
	v_rcp_f32_e32 v48, v48
	v_rcp_f32_e32 v49, v49
	v_rcp_f32_e32 v55, v51
	v_pk_mul_f32 v[34:35], v[34:35], v[52:53] op_sel_hi:[1,0]
	v_pk_mul_f32 v[36:37], v[36:37], v[52:53] op_sel_hi:[1,0]
	v_pk_mul_f32 v[42:43], v[42:43], v[52:53] op_sel_hi:[1,0]
	v_pk_mul_f32 v[44:45], v[44:45], v[52:53] op_sel_hi:[1,0]
	v_pk_mul_f32 v[38:39], v[36:37], v[48:49]
	v_pk_mul_f32 v[36:37], v[34:35], v[46:47]
	v_pk_mul_f32 v[44:45], v[44:45], v[54:55]
	v_pk_mul_f32 v[42:43], v[42:43], v[56:57]
	v_add_u32_e32 v40, 0x90, v134
	v_cvt_pk_bf16_f32 v34, v42, v43
	v_cvt_pk_bf16_f32 v35, v44, v45
	v_cvt_pk_bf16_f32 v36, v36, v37
	v_cvt_pk_bf16_f32 v37, v38, v39
	v_fmamk_f32 v38, v125, 0x39800000, v144
	v_rsq_f32_e32 v41, v38
	v_mad_i64_i32 v[38:39], s[18:19], v40, s62, v[122:123]
	v_lshl_add_u64 v[38:39], v[38:39], 0, v[108:109]
	global_store_dwordx4 v[38:39], v[34:37], off nt
	s_nop 1
	v_mul_f32_e32 v34, 0xbfb8aa3b, v41
	v_pk_mul_f32 v[36:37], v[30:31], v[34:35] op_sel_hi:[1,0]
	s_nop 0
	v_exp_f32_e32 v35, v36
	v_exp_f32_e32 v37, v37
	v_mul_f32_e32 v36, v41, v41
	v_pk_mul_f32 v[38:39], v[32:33], v[34:35] op_sel_hi:[1,0]
	v_add_f32_e32 v35, 1.0, v35
	v_rcp_f32_e32 v40, v35
	v_exp_f32_e32 v35, v38
	v_exp_f32_e32 v39, v39
	v_add_f32_e32 v37, 1.0, v37
	v_rcp_f32_e32 v41, v37
	v_add_f32_e32 v35, 1.0, v35
	v_rcp_f32_e32 v38, v35
	v_add_f32_e32 v35, 1.0, v39
	v_pk_mul_f32 v[30:31], v[22:23], v[34:35] op_sel_hi:[1,0]
	v_pk_mul_f32 v[32:33], v[24:25], v[34:35] op_sel_hi:[1,0]
	v_exp_f32_e32 v30, v30
	v_exp_f32_e32 v31, v31
	v_exp_f32_e32 v32, v32
	v_exp_f32_e32 v33, v33
	v_add_f32_e32 v30, 1.0, v30
	v_add_f32_e32 v31, 1.0, v31
	v_add_f32_e32 v32, 1.0, v32
	v_add_f32_e32 v33, 1.0, v33
	v_rcp_f32_e32 v30, v30
	v_rcp_f32_e32 v31, v31
	v_rcp_f32_e32 v32, v32
	v_rcp_f32_e32 v33, v33
	v_rcp_f32_e32 v39, v35
	v_pk_mul_f32 v[18:19], v[18:19], v[36:37] op_sel_hi:[1,0]
	v_pk_mul_f32 v[20:21], v[20:21], v[36:37] op_sel_hi:[1,0]
	v_pk_mul_f32 v[26:27], v[26:27], v[36:37] op_sel_hi:[1,0]
	v_pk_mul_f32 v[28:29], v[28:29], v[36:37] op_sel_hi:[1,0]
	v_pk_mul_f32 v[22:23], v[20:21], v[32:33]
	v_pk_mul_f32 v[20:21], v[18:19], v[30:31]
	v_pk_mul_f32 v[28:29], v[28:29], v[38:39]
	v_pk_mul_f32 v[26:27], v[26:27], v[40:41]
	v_add_u32_e32 v24, 0xa0, v134
	v_cvt_pk_bf16_f32 v18, v26, v27
	v_cvt_pk_bf16_f32 v19, v28, v29
	v_cvt_pk_bf16_f32 v20, v20, v21
	v_cvt_pk_bf16_f32 v21, v22, v23
	v_fmamk_f32 v22, v124, 0x39800000, v144
	v_rsq_f32_e32 v25, v22
	v_mad_i64_i32 v[22:23], s[18:19], v24, s62, v[122:123]
	v_lshl_add_u64 v[22:23], v[22:23], 0, v[108:109]
	global_store_dwordx4 v[22:23], v[18:21], off nt
	s_nop 1
	v_mul_f32_e32 v18, 0xbfb8aa3b, v25
	v_pk_mul_f32 v[20:21], v[14:15], v[18:19] op_sel_hi:[1,0]
	s_nop 0
	v_exp_f32_e32 v19, v20
	v_exp_f32_e32 v21, v21
	v_mul_f32_e32 v20, v25, v25
	v_pk_mul_f32 v[22:23], v[16:17], v[18:19] op_sel_hi:[1,0]
	v_add_f32_e32 v19, 1.0, v19
	v_rcp_f32_e32 v24, v19
	v_exp_f32_e32 v19, v22
	v_exp_f32_e32 v23, v23
	v_add_f32_e32 v21, 1.0, v21
	v_rcp_f32_e32 v25, v21
	v_add_f32_e32 v19, 1.0, v19
	v_rcp_f32_e32 v22, v19
	v_add_f32_e32 v19, 1.0, v23
	v_pk_mul_f32 v[14:15], v[6:7], v[18:19] op_sel_hi:[1,0]
	v_pk_mul_f32 v[16:17], v[8:9], v[18:19] op_sel_hi:[1,0]
	v_exp_f32_e32 v14, v14
	v_exp_f32_e32 v15, v15
	v_exp_f32_e32 v16, v16
	v_exp_f32_e32 v17, v17
	v_add_f32_e32 v14, 1.0, v14
	v_add_f32_e32 v15, 1.0, v15
	v_add_f32_e32 v16, 1.0, v16
	v_add_f32_e32 v17, 1.0, v17
	v_rcp_f32_e32 v14, v14
	v_rcp_f32_e32 v15, v15
	v_rcp_f32_e32 v16, v16
	v_rcp_f32_e32 v17, v17
	v_rcp_f32_e32 v23, v19
	v_pk_mul_f32 v[2:3], v[2:3], v[20:21] op_sel_hi:[1,0]
	v_pk_mul_f32 v[4:5], v[4:5], v[20:21] op_sel_hi:[1,0]
	v_pk_mul_f32 v[10:11], v[10:11], v[20:21] op_sel_hi:[1,0]
	v_pk_mul_f32 v[12:13], v[12:13], v[20:21] op_sel_hi:[1,0]
	v_pk_mul_f32 v[6:7], v[4:5], v[16:17]
	v_pk_mul_f32 v[4:5], v[2:3], v[14:15]
	v_add_u32_e32 v8, 0xb0, v134
	v_pk_mul_f32 v[12:13], v[12:13], v[22:23]
	v_pk_mul_f32 v[10:11], v[10:11], v[24:25]
	s_nop 0
	v_cvt_pk_bf16_f32 v2, v10, v11
	v_cvt_pk_bf16_f32 v3, v12, v13
	v_cvt_pk_bf16_f32 v4, v4, v5
	v_cvt_pk_bf16_f32 v5, v6, v7
	v_mad_i64_i32 v[6:7], s[18:19], v8, s62, v[122:123]
	v_lshl_add_u64 v[6:7], v[6:7], 0, v[108:109]
	global_store_dwordx4 v[6:7], v[2:5], off nt
	s_cbranch_vccnz .LBB0_637
	s_andn2_b64 vcc, exec, s[34:35]
	s_cbranch_vccnz .LBB0_636
	s_barrier
	s_branch .LBB0_636
